# combine chain: S_new store address computed in the MFMA shadow instead of on the post-MFMA tail
# baseline (speedup 1.0000x reference)
.LBB0_500:
	s_min_u32 s2, s12, 0x76
	s_mulk_i32 s2, 0x6000
	s_lshl_b32 s10, s2, 2
	s_mov_b32 s11, s73
	s_waitcnt lgkmcnt(0)
	s_barrier
	global_load_dwordx4 v[58:61], v[244:245], off
	s_waitcnt vmcnt(16)
	ds_write_b128 v81, v[14:17]
	ds_write_b128 v81, v[10:13] offset:16
	v_lshl_add_u64 v[10:11], v[90:91], 0, s[10:11]
	s_mov_b64 s[16:17], 0xc0000
	v_lshl_add_u64 v[12:13], v[10:11], 0, s[16:17]
	v_add_co_u32_e32 v10, vcc, 0xc0000, v10
	v_lshl_add_u64 v[244:245], v[88:89], 0, s[72:73]
	s_nop 0
	v_addc_co_u32_e32 v11, vcc, 0, v11, vcc
	v_add_co_u32_e32 v244, vcc, 0xa8000, v244
	global_load_dwordx4 v[14:17], v[10:11], off
	s_nop 0
	global_load_dwordx4 v[10:13], v[12:13], off offset:16
	v_addc_co_u32_e32 v245, vcc, 0, v245, vcc
	s_and_b64 vcc, exec, s[6:7]
	v_add_u32_e32 v0, 0x8000, v179
	s_cbranch_vccnz .LBB0_502
	ds_read2st64_b32 v[200:201], v175 offset0:64 offset1:68
	ds_read2st64_b32 v[216:217], v176 offset0:144 offset1:145
	ds_read2st64_b32 v[202:203], v175 offset0:72 offset1:76
	ds_read2st64_b32 v[218:219], v176 offset0:146 offset1:147
	ds_read2st64_b32 v[204:205], v175 offset0:80 offset1:84
	ds_read2st64_b32 v[220:221], v176 offset0:148 offset1:149
	ds_read2st64_b32 v[206:207], v175 offset0:88 offset1:92
	ds_read2st64_b32 v[222:223], v176 offset0:150 offset1:151
	ds_read2st64_b32 v[208:209], v175 offset0:96 offset1:100
	ds_read2st64_b32 v[224:225], v176 offset0:152 offset1:153
	ds_read2st64_b32 v[210:211], v175 offset0:104 offset1:108
	ds_read2st64_b32 v[226:227], v176 offset0:154 offset1:155
	s_waitcnt vmcnt(16) lgkmcnt(10)
	v_mfma_f32_16x16x4_f32 v[66:69], v200, v216, v[66:69]
	v_mfma_f32_16x16x4_f32 v[94:97], v201, v217, 0
	ds_read2st64_b32 v[212:213], v175 offset0:112 offset1:116
	ds_read2st64_b32 v[228:229], v176 offset0:156 offset1:157
	s_waitcnt lgkmcnt(10)
	v_mfma_f32_16x16x4_f32 v[66:69], v202, v218, v[66:69]
	v_mfma_f32_16x16x4_f32 v[94:97], v203, v219, v[94:97]
	ds_read2st64_b32 v[214:215], v175 offset0:120 offset1:124
	ds_read2st64_b32 v[230:231], v176 offset0:158 offset1:159
	s_waitcnt lgkmcnt(10)
	v_mfma_f32_16x16x4_f32 v[66:69], v204, v220, v[66:69]
	v_mfma_f32_16x16x4_f32 v[94:97], v205, v221, v[94:97]
	s_waitcnt lgkmcnt(8)
	v_mfma_f32_16x16x4_f32 v[66:69], v206, v222, v[66:69]
	v_mfma_f32_16x16x4_f32 v[94:97], v207, v223, v[94:97]
	s_waitcnt lgkmcnt(6)
	v_mfma_f32_16x16x4_f32 v[66:69], v208, v224, v[66:69]
	v_mfma_f32_16x16x4_f32 v[94:97], v209, v225, v[94:97]
	s_waitcnt lgkmcnt(4)
	v_mfma_f32_16x16x4_f32 v[66:69], v210, v226, v[66:69]
	v_mfma_f32_16x16x4_f32 v[94:97], v211, v227, v[94:97]
	s_waitcnt lgkmcnt(2)
	v_mfma_f32_16x16x4_f32 v[66:69], v212, v228, v[66:69]
	v_mfma_f32_16x16x4_f32 v[94:97], v213, v229, v[94:97]
	s_waitcnt lgkmcnt(0)
	v_mfma_f32_16x16x4_f32 v[66:69], v214, v230, v[66:69]
	v_mfma_f32_16x16x4_f32 v[94:97], v215, v231, v[94:97]
	v_add_co_u32_e32 v246, vcc, 0x18000, v92
	s_nop 0
	v_addc_co_u32_e32 v247, vcc, 0, v93, vcc
	s_nop 9
	v_pk_add_f32 v[66:67], v[66:67], v[94:95]
	v_pk_add_f32 v[68:69], v[68:69], v[96:97]
	global_store_dwordx4 v[246:247], v[66:69], off
	ds_write2_b32 v0, v66, v67 offset1:16
	ds_write2_b32 v0, v68, v69 offset0:32 offset1:48
.LBB0_502:
	s_min_u32 s2, s12, 0x75
	s_mulk_i32 s2, 0x6000
	s_lshl_b32 s72, s2, 2
	s_waitcnt lgkmcnt(0)
	s_barrier
	global_load_dwordx4 v[66:69], v[244:245], off
	s_waitcnt vmcnt(17)
	ds_write_b128 v81, v[18:21] offset:16384
	s_waitcnt vmcnt(16)
	ds_write_b128 v81, v[22:25] offset:16400
	v_lshl_add_u64 v[18:19], v[90:91], 0, s[72:73]
	s_mov_b64 s[16:17], 0xd8000
	v_lshl_add_u64 v[22:23], v[18:19], 0, s[16:17]
	v_add_co_u32_e32 v18, vcc, 0xd8000, v18
	v_lshl_add_u64 v[244:245], v[88:89], 0, s[10:11]
	s_nop 0
	v_addc_co_u32_e32 v19, vcc, 0, v19, vcc
	v_add_co_u32_e32 v244, vcc, 0xc0000, v244
	global_load_dwordx4 v[18:21], v[18:19], off
	s_nop 0
	global_load_dwordx4 v[22:25], v[22:23], off offset:16
	v_addc_co_u32_e32 v245, vcc, 0, v245, vcc
	s_and_b64 vcc, exec, s[6:7]
	s_cbranch_vccnz .LBB0_504
	ds_read2st64_b32 v[200:201], v175 offset1:4
	ds_read2st64_b32 v[216:217], v176 offset0:128 offset1:129
	ds_read2st64_b32 v[202:203], v175 offset0:8 offset1:12
	ds_read2st64_b32 v[218:219], v176 offset0:130 offset1:131
	ds_read2st64_b32 v[204:205], v175 offset0:16 offset1:20
	ds_read2st64_b32 v[220:221], v176 offset0:132 offset1:133
	ds_read2st64_b32 v[206:207], v175 offset0:24 offset1:28
	ds_read2st64_b32 v[222:223], v176 offset0:134 offset1:135
	ds_read2st64_b32 v[208:209], v175 offset0:32 offset1:36
	ds_read2st64_b32 v[224:225], v176 offset0:136 offset1:137
	ds_read2st64_b32 v[210:211], v175 offset0:40 offset1:44
	ds_read2st64_b32 v[226:227], v176 offset0:138 offset1:139
	s_waitcnt vmcnt(16) lgkmcnt(10)
	v_mfma_f32_16x16x4_f32 v[74:77], v200, v216, v[74:77]
	v_mfma_f32_16x16x4_f32 v[94:97], v201, v217, 0
	ds_read2st64_b32 v[212:213], v175 offset0:48 offset1:52
	ds_read2st64_b32 v[228:229], v176 offset0:140 offset1:141
	s_waitcnt lgkmcnt(10)
	v_mfma_f32_16x16x4_f32 v[74:77], v202, v218, v[74:77]
	v_mfma_f32_16x16x4_f32 v[94:97], v203, v219, v[94:97]
	ds_read2st64_b32 v[214:215], v175 offset0:56 offset1:60
	ds_read2st64_b32 v[230:231], v176 offset0:142 offset1:143
	s_waitcnt lgkmcnt(10)
	v_mfma_f32_16x16x4_f32 v[74:77], v204, v220, v[74:77]
	v_mfma_f32_16x16x4_f32 v[94:97], v205, v221, v[94:97]
	s_waitcnt lgkmcnt(8)
	v_mfma_f32_16x16x4_f32 v[74:77], v206, v222, v[74:77]
	v_mfma_f32_16x16x4_f32 v[94:97], v207, v223, v[94:97]
	s_waitcnt lgkmcnt(6)
	v_mfma_f32_16x16x4_f32 v[74:77], v208, v224, v[74:77]
	v_mfma_f32_16x16x4_f32 v[94:97], v209, v225, v[94:97]
	s_waitcnt lgkmcnt(4)
	v_mfma_f32_16x16x4_f32 v[74:77], v210, v226, v[74:77]
	v_mfma_f32_16x16x4_f32 v[94:97], v211, v227, v[94:97]
	s_waitcnt lgkmcnt(2)
	v_mfma_f32_16x16x4_f32 v[74:77], v212, v228, v[74:77]
	v_mfma_f32_16x16x4_f32 v[94:97], v213, v229, v[94:97]
	s_waitcnt lgkmcnt(0)
	v_mfma_f32_16x16x4_f32 v[74:77], v214, v230, v[74:77]
	v_mfma_f32_16x16x4_f32 v[94:97], v215, v231, v[94:97]
	v_add_co_u32_e32 v246, vcc, 0x30000, v92
	s_nop 0
	v_addc_co_u32_e32 v247, vcc, 0, v93, vcc
	s_nop 9
	v_pk_add_f32 v[74:75], v[74:75], v[94:95]
	v_pk_add_f32 v[76:77], v[76:77], v[96:97]
	global_store_dwordx4 v[246:247], v[74:77], off
	v_add_u32_e32 v94, 0x9000, v179
	ds_write2_b32 v94, v74, v75 offset1:16
	ds_write2_b32 v94, v76, v77 offset0:32 offset1:48
.LBB0_504:
	s_min_u32 s2, s12, 0x74
	s_mulk_i32 s2, 0x6000
	s_lshl_b32 s10, s2, 2
	s_mov_b32 s11, s73
	s_waitcnt lgkmcnt(0)
	s_barrier
	global_load_dwordx4 v[74:77], v[244:245], off
	s_waitcnt vmcnt(16)
	ds_write_b128 v81, v[30:33]
	ds_write_b128 v81, v[26:29] offset:16
	v_lshl_add_u64 v[26:27], v[90:91], 0, s[10:11]
	s_mov_b64 s[16:17], 0xf0000
	v_lshl_add_u64 v[28:29], v[26:27], 0, s[16:17]
	v_add_co_u32_e32 v26, vcc, 0xf0000, v26
	v_lshl_add_u64 v[244:245], v[88:89], 0, s[72:73]
	s_nop 0
	v_addc_co_u32_e32 v27, vcc, 0, v27, vcc
	v_add_co_u32_e32 v244, vcc, 0xd8000, v244
	global_load_dwordx4 v[30:33], v[26:27], off
	s_nop 0
	global_load_dwordx4 v[26:29], v[28:29], off offset:16
	v_addc_co_u32_e32 v245, vcc, 0, v245, vcc
	s_and_b64 vcc, exec, s[6:7]
	s_cbranch_vccnz .LBB0_506
	ds_read2st64_b32 v[200:201], v175 offset0:64 offset1:68
	ds_read2st64_b32 v[216:217], v176 offset0:144 offset1:145
	ds_read2st64_b32 v[202:203], v175 offset0:72 offset1:76
	ds_read2st64_b32 v[218:219], v176 offset0:146 offset1:147
	ds_read2st64_b32 v[204:205], v175 offset0:80 offset1:84
	ds_read2st64_b32 v[220:221], v176 offset0:148 offset1:149
	ds_read2st64_b32 v[206:207], v175 offset0:88 offset1:92
	ds_read2st64_b32 v[222:223], v176 offset0:150 offset1:151
	ds_read2st64_b32 v[208:209], v175 offset0:96 offset1:100
	ds_read2st64_b32 v[224:225], v176 offset0:152 offset1:153
	ds_read2st64_b32 v[210:211], v175 offset0:104 offset1:108
	ds_read2st64_b32 v[226:227], v176 offset0:154 offset1:155
	s_waitcnt vmcnt(16) lgkmcnt(10)
	v_mfma_f32_16x16x4_f32 v[70:73], v200, v216, v[70:73]
	v_mfma_f32_16x16x4_f32 v[94:97], v201, v217, 0
	ds_read2st64_b32 v[212:213], v175 offset0:112 offset1:116
	ds_read2st64_b32 v[228:229], v176 offset0:156 offset1:157
	s_waitcnt lgkmcnt(10)
	v_mfma_f32_16x16x4_f32 v[70:73], v202, v218, v[70:73]
	v_mfma_f32_16x16x4_f32 v[94:97], v203, v219, v[94:97]
	ds_read2st64_b32 v[214:215], v175 offset0:120 offset1:124
	ds_read2st64_b32 v[230:231], v176 offset0:158 offset1:159
	s_waitcnt lgkmcnt(10)
	v_mfma_f32_16x16x4_f32 v[70:73], v204, v220, v[70:73]
	v_mfma_f32_16x16x4_f32 v[94:97], v205, v221, v[94:97]
	s_waitcnt lgkmcnt(8)
	v_mfma_f32_16x16x4_f32 v[70:73], v206, v222, v[70:73]
	v_mfma_f32_16x16x4_f32 v[94:97], v207, v223, v[94:97]
	s_waitcnt lgkmcnt(6)
	v_mfma_f32_16x16x4_f32 v[70:73], v208, v224, v[70:73]
	v_mfma_f32_16x16x4_f32 v[94:97], v209, v225, v[94:97]
	s_waitcnt lgkmcnt(4)
	v_mfma_f32_16x16x4_f32 v[70:73], v210, v226, v[70:73]
	v_mfma_f32_16x16x4_f32 v[94:97], v211, v227, v[94:97]
	s_waitcnt lgkmcnt(2)
	v_mfma_f32_16x16x4_f32 v[70:73], v212, v228, v[70:73]
	v_mfma_f32_16x16x4_f32 v[94:97], v213, v229, v[94:97]
	s_waitcnt lgkmcnt(0)
	v_mfma_f32_16x16x4_f32 v[70:73], v214, v230, v[70:73]
	v_mfma_f32_16x16x4_f32 v[94:97], v215, v231, v[94:97]
	v_add_co_u32_e32 v246, vcc, 0x48000, v92
	s_nop 0
	v_addc_co_u32_e32 v247, vcc, 0, v93, vcc
	s_nop 9
	v_pk_add_f32 v[70:71], v[70:71], v[94:95]
	v_pk_add_f32 v[72:73], v[72:73], v[96:97]
	global_store_dwordx4 v[246:247], v[70:73], off
	ds_write2_b32 v0, v70, v71 offset1:16
	ds_write2_b32 v0, v72, v73 offset0:32 offset1:48
.LBB0_506:
	s_min_u32 s2, s12, 0x73
	s_mulk_i32 s2, 0x6000
	s_lshl_b32 s72, s2, 2
	s_waitcnt lgkmcnt(0)
	s_barrier
	global_load_dwordx4 v[70:73], v[244:245], off
	s_waitcnt vmcnt(17)
	ds_write_b128 v81, v[34:37] offset:16384
	s_waitcnt vmcnt(16)
	ds_write_b128 v81, v[38:41] offset:16400
	v_lshl_add_u64 v[34:35], v[90:91], 0, s[72:73]
	s_mov_b64 s[16:17], 0x108000
	v_lshl_add_u64 v[38:39], v[34:35], 0, s[16:17]
	v_add_co_u32_e32 v34, vcc, 0x108000, v34
	v_lshl_add_u64 v[244:245], v[88:89], 0, s[10:11]
	s_nop 0
	v_addc_co_u32_e32 v35, vcc, 0, v35, vcc
	v_add_co_u32_e32 v244, vcc, 0xf0000, v244
	global_load_dwordx4 v[34:37], v[34:35], off
	s_nop 0
	global_load_dwordx4 v[38:41], v[38:39], off offset:16
	v_addc_co_u32_e32 v245, vcc, 0, v245, vcc
	s_and_b64 vcc, exec, s[6:7]
	s_cbranch_vccnz .LBB0_508
	ds_read2st64_b32 v[200:201], v175 offset1:4
	ds_read2st64_b32 v[216:217], v176 offset0:128 offset1:129
	ds_read2st64_b32 v[202:203], v175 offset0:8 offset1:12
	ds_read2st64_b32 v[218:219], v176 offset0:130 offset1:131
	ds_read2st64_b32 v[204:205], v175 offset0:16 offset1:20
	ds_read2st64_b32 v[220:221], v176 offset0:132 offset1:133
	ds_read2st64_b32 v[206:207], v175 offset0:24 offset1:28
	ds_read2st64_b32 v[222:223], v176 offset0:134 offset1:135
	ds_read2st64_b32 v[208:209], v175 offset0:32 offset1:36
	ds_read2st64_b32 v[224:225], v176 offset0:136 offset1:137
	ds_read2st64_b32 v[210:211], v175 offset0:40 offset1:44
	ds_read2st64_b32 v[226:227], v176 offset0:138 offset1:139
	s_waitcnt vmcnt(16) lgkmcnt(10)
	v_mfma_f32_16x16x4_f32 v[62:65], v200, v216, v[62:65]
	v_mfma_f32_16x16x4_f32 v[94:97], v201, v217, 0
	ds_read2st64_b32 v[212:213], v175 offset0:48 offset1:52
	ds_read2st64_b32 v[228:229], v176 offset0:140 offset1:141
	s_waitcnt lgkmcnt(10)
	v_mfma_f32_16x16x4_f32 v[62:65], v202, v218, v[62:65]
	v_mfma_f32_16x16x4_f32 v[94:97], v203, v219, v[94:97]
	ds_read2st64_b32 v[214:215], v175 offset0:56 offset1:60
	ds_read2st64_b32 v[230:231], v176 offset0:142 offset1:143
	s_waitcnt lgkmcnt(10)
	v_mfma_f32_16x16x4_f32 v[62:65], v204, v220, v[62:65]
	v_mfma_f32_16x16x4_f32 v[94:97], v205, v221, v[94:97]
	s_waitcnt lgkmcnt(8)
	v_mfma_f32_16x16x4_f32 v[62:65], v206, v222, v[62:65]
	v_mfma_f32_16x16x4_f32 v[94:97], v207, v223, v[94:97]
	s_waitcnt lgkmcnt(6)
	v_mfma_f32_16x16x4_f32 v[62:65], v208, v224, v[62:65]
	v_mfma_f32_16x16x4_f32 v[94:97], v209, v225, v[94:97]
	s_waitcnt lgkmcnt(4)
	v_mfma_f32_16x16x4_f32 v[62:65], v210, v226, v[62:65]
	v_mfma_f32_16x16x4_f32 v[94:97], v211, v227, v[94:97]
	s_waitcnt lgkmcnt(2)
	v_mfma_f32_16x16x4_f32 v[62:65], v212, v228, v[62:65]
	v_mfma_f32_16x16x4_f32 v[94:97], v213, v229, v[94:97]
	s_waitcnt lgkmcnt(0)
	v_mfma_f32_16x16x4_f32 v[62:65], v214, v230, v[62:65]
	v_mfma_f32_16x16x4_f32 v[94:97], v215, v231, v[94:97]
	v_add_co_u32_e32 v246, vcc, 0x60000, v92
	s_nop 0
	v_addc_co_u32_e32 v247, vcc, 0, v93, vcc
	s_nop 9
	v_pk_add_f32 v[62:63], v[62:63], v[94:95]
	v_pk_add_f32 v[64:65], v[64:65], v[96:97]
	global_store_dwordx4 v[246:247], v[62:65], off
	v_add_u32_e32 v94, 0x9000, v179
	ds_write2_b32 v94, v62, v63 offset1:16
	ds_write2_b32 v94, v64, v65 offset0:32 offset1:48
.LBB0_508:
	s_min_u32 s2, s12, 0x72
	s_mul_i32 s10, s2, 0x18000
	s_mov_b32 s11, s73
	s_waitcnt lgkmcnt(0)
	s_barrier
	global_load_dwordx4 v[62:65], v[244:245], off
	s_waitcnt vmcnt(16)
	ds_write_b128 v81, v[46:49]
	ds_write_b128 v81, v[42:45] offset:16
	v_lshl_add_u64 v[42:43], v[90:91], 0, s[10:11]
	s_mov_b64 s[10:11], 0x120000
	v_lshl_add_u64 v[44:45], v[42:43], 0, s[10:11]
	v_add_co_u32_e32 v42, vcc, 0x120000, v42
	v_lshl_add_u64 v[244:245], v[88:89], 0, s[72:73]
	s_nop 0
	v_addc_co_u32_e32 v43, vcc, 0, v43, vcc
	v_add_co_u32_e32 v244, vcc, 0x108000, v244
	global_load_dwordx4 v[46:49], v[42:43], off
	s_nop 0
	global_load_dwordx4 v[42:45], v[44:45], off offset:16
	v_addc_co_u32_e32 v245, vcc, 0, v245, vcc
	s_and_b64 vcc, exec, s[6:7]
	s_cbranch_vccnz .LBB0_510
	ds_read2st64_b32 v[200:201], v175 offset0:64 offset1:68
	ds_read2st64_b32 v[216:217], v176 offset0:144 offset1:145
	ds_read2st64_b32 v[202:203], v175 offset0:72 offset1:76
	ds_read2st64_b32 v[218:219], v176 offset0:146 offset1:147
	ds_read2st64_b32 v[204:205], v175 offset0:80 offset1:84
	ds_read2st64_b32 v[220:221], v176 offset0:148 offset1:149
	ds_read2st64_b32 v[206:207], v175 offset0:88 offset1:92
	ds_read2st64_b32 v[222:223], v176 offset0:150 offset1:151
	ds_read2st64_b32 v[208:209], v175 offset0:96 offset1:100
	ds_read2st64_b32 v[224:225], v176 offset0:152 offset1:153
	ds_read2st64_b32 v[210:211], v175 offset0:104 offset1:108
	ds_read2st64_b32 v[226:227], v176 offset0:154 offset1:155
	s_waitcnt vmcnt(16) lgkmcnt(10)
	v_mfma_f32_16x16x4_f32 v[54:57], v200, v216, v[54:57]
	v_mfma_f32_16x16x4_f32 v[94:97], v201, v217, 0
	ds_read2st64_b32 v[212:213], v175 offset0:112 offset1:116
	ds_read2st64_b32 v[228:229], v176 offset0:156 offset1:157
	s_waitcnt lgkmcnt(10)
	v_mfma_f32_16x16x4_f32 v[54:57], v202, v218, v[54:57]
	v_mfma_f32_16x16x4_f32 v[94:97], v203, v219, v[94:97]
	ds_read2st64_b32 v[214:215], v175 offset0:120 offset1:124
	ds_read2st64_b32 v[230:231], v176 offset0:158 offset1:159
	s_waitcnt lgkmcnt(10)
	v_mfma_f32_16x16x4_f32 v[54:57], v204, v220, v[54:57]
	v_mfma_f32_16x16x4_f32 v[94:97], v205, v221, v[94:97]
	s_waitcnt lgkmcnt(8)
	v_mfma_f32_16x16x4_f32 v[54:57], v206, v222, v[54:57]
	v_mfma_f32_16x16x4_f32 v[94:97], v207, v223, v[94:97]
	s_waitcnt lgkmcnt(6)
	v_mfma_f32_16x16x4_f32 v[54:57], v208, v224, v[54:57]
	v_mfma_f32_16x16x4_f32 v[94:97], v209, v225, v[94:97]
	s_waitcnt lgkmcnt(4)
	v_mfma_f32_16x16x4_f32 v[54:57], v210, v226, v[54:57]
	v_mfma_f32_16x16x4_f32 v[94:97], v211, v227, v[94:97]
	s_waitcnt lgkmcnt(2)
	v_mfma_f32_16x16x4_f32 v[54:57], v212, v228, v[54:57]
	v_mfma_f32_16x16x4_f32 v[94:97], v213, v229, v[94:97]
	s_waitcnt lgkmcnt(0)
	v_mfma_f32_16x16x4_f32 v[54:57], v214, v230, v[54:57]
	v_mfma_f32_16x16x4_f32 v[94:97], v215, v231, v[94:97]
	v_add_co_u32_e32 v246, vcc, 0x78000, v92
	s_nop 0
	v_addc_co_u32_e32 v247, vcc, 0, v93, vcc
	s_nop 9
	v_pk_add_f32 v[54:55], v[54:55], v[94:95]
	v_pk_add_f32 v[56:57], v[56:57], v[96:97]
	global_store_dwordx4 v[246:247], v[54:57], off
	ds_write2_b32 v0, v54, v55 offset1:16
	ds_write2_b32 v0, v56, v57 offset0:32 offset1:48
